# also K-split the fused last-layer FFN-out sample-path sgemm unit across workgroup pairs
# speedup vs baseline: 1.0134x; 1.0052x over previous
.LBB0_2908:
	s_and_b64 vcc, exec, s[2:3]
	s_cbranch_vccz .LBB0_2985
	v_lshlrev_b32_e32 v0, 4, v26
	s_waitcnt lgkmcnt(0)
	v_add_u32_e32 v1, 0x2000, v0
	v_ashrrev_i32_e32 v2, 31, v1
	v_lshrrev_b32_e32 v2, 22, v2
	v_add_u32_e32 v2, v1, v2
	v_ashrrev_i32_e32 v28, 10, v2
	v_mul_i32_i24_e32 v2, 0x400, v28
	v_sub_u32_e32 v1, v1, v2
	v_lshrrev_b32_e32 v2, 4, v1
	v_bitop3_b32 v1, v2, v1, 32 bitop3:0x6c
	v_ashrrev_i32_e32 v2, 31, v1
	v_lshrrev_b32_e32 v2, 26, v2
	v_add_u32_e32 v2, v1, v2
	v_lshlrev_b32_e32 v3, 3, v28
	v_ashrrev_i32_e32 v29, 6, v2
	v_and_b32_e32 v3, -16, v3
	v_add_u32_e32 v3, v29, v3
	v_and_b32_e32 v4, 3, v29
	s_mov_b32 s1, 0xffffe0
	v_lshrrev_b32_e32 v5, 2, v3
	v_lshlrev_b32_e32 v6, 1, v3
	v_and_b32_e32 v2, 0xc0, v2
	v_and_or_b32 v4, v3, s1, v4
	v_and_b32_e32 v5, 4, v5
	v_and_b32_e32 v6, 24, v6
	v_sub_u32_e32 v1, v1, v2
	v_or3_b32 v4, v4, v5, v6
	v_lshlrev_b32_e32 v5, 5, v28
	v_ashrrev_i16_sdwa v1, v215, sext(v1) dst_sel:DWORD dst_unused:UNUSED_PAD src0_sel:DWORD src1_sel:BYTE_0
	v_and_b32_e32 v30, 32, v5
	v_bfe_i32 v31, v1, 0, 16
	s_movk_i32 s0, 0xb00
	v_mul_u32_u24_e32 v4, 0xb00, v4
	v_add_u32_e32 v1, v30, v31
	v_mul_lo_u32 v2, v3, s0
	v_add_lshl_u32 v130, v4, v1, 1
	v_add_lshl_u32 v132, v1, v2, 1
	v_bfe_i32 v1, v26, 27, 1
	v_lshrrev_b32_e32 v1, 22, v1
	v_add_u32_e32 v1, v0, v1
	v_and_b32_e32 v1, 0xfffffc00, v1
	v_sub_u32_e32 v0, v0, v1
	v_lshrrev_b32_e32 v1, 4, v0
	v_ashrrev_i32_e32 v2, 31, v26
	v_bitop3_b32 v0, v1, v0, 32 bitop3:0x6c
	v_lshrrev_b32_e32 v2, 26, v2
	v_ashrrev_i32_e32 v1, 31, v0
	v_add_u32_e32 v2, v26, v2
	v_lshrrev_b32_e32 v1, 26, v1
	v_ashrrev_i32_e32 v35, 6, v2
	v_add_u32_e32 v1, v0, v1
	v_lshlrev_b32_e32 v2, 3, v35
	v_ashrrev_i32_e32 v34, 6, v1
	v_and_b32_e32 v2, -16, v2
	v_add_u32_e32 v2, v34, v2
	v_and_b32_e32 v3, 3, v34
	v_lshrrev_b32_e32 v4, 2, v2
	v_lshlrev_b32_e32 v5, 1, v2
	v_and_b32_e32 v1, 0xc0, v1
	s_ashr_i32 s19, s8, 6
	v_and_or_b32 v3, v2, s1, v3
	v_and_b32_e32 v4, 4, v4
	v_and_b32_e32 v5, 24, v5
	v_sub_u32_e32 v0, v0, v1
	s_lshl_b32 s11, s19, 10
	v_or3_b32 v3, v3, v4, v5
	v_lshlrev_b32_e32 v4, 5, v35
	v_ashrrev_i16_sdwa v0, v215, sext(v0) dst_sel:DWORD dst_unused:UNUSED_PAD src0_sel:DWORD src1_sel:BYTE_0
	v_mul_lo_u32 v1, v2, s0
	v_readlane_b32 s0, v254, 19
	v_and_b32_e32 v36, 32, v4
	v_bfe_i32 v37, v0, 0, 16
	s_add_u32 s52, s77, s0
	v_readlane_b32 s0, v254, 17
	v_mul_u32_u24_e32 v3, 0xb00, v3
	v_add_u32_e32 v0, v36, v37
	s_addc_u32 s53, s78, s0
	s_add_i32 s12, s11, 0
	v_add_lshl_u32 v32, v3, v0, 1
	s_add_i32 m0, s12, 0x10000
	v_readlane_b32 s0, v254, 16
	global_load_lds_dwordx4 v32, s[52:53]
	s_add_i32 m0, s12, 0x12000
	s_add_u32 s2, s52, 0xb0000
	global_load_lds_dwordx4 v130, s[52:53]
	s_addc_u32 s3, s53, 0
	s_add_i32 m0, s12, 0x14000
	v_add_lshl_u32 v134, v0, v1, 1
	global_load_lds_dwordx4 v32, s[2:3]
	s_add_i32 m0, s12, 0x16000
	s_add_u32 s40, s75, s0
	v_readlane_b32 s0, v254, 13
	s_addc_u32 s41, s76, s0
	s_add_i32 s14, s12, 0x2000
	global_load_lds_dwordx4 v130, s[2:3]
	s_mov_b32 m0, s12
	s_add_u32 s2, s40, 0xb0000
	global_load_lds_dwordx4 v134, s[40:41]
	s_mov_b32 m0, s14
	s_addc_u32 s3, s41, 0
	s_add_i32 s15, s12, 0x4000
	global_load_lds_dwordx4 v132, s[40:41]
	s_mov_b32 m0, s15
	s_add_i32 s17, s12, 0x6000
	global_load_lds_dwordx4 v134, s[2:3]
	s_mov_b32 m0, s17
	v_and_b32_e32 v145, 64, v216
	global_load_lds_dwordx4 v132, s[2:3]
	s_ashr_i32 s2, s37, 31
	s_lshr_b32 s2, s2, 24
	s_add_i32 s2, s37, s2
	s_and_b32 s2, s2, 0xffffff00
	s_sub_i32 s13, s37, s2
	s_mov_b32 s100, 0
	s_mov_b32 s101, 0
	s_cmp_gt_i32 s13, 31
	v_xor_b32_e32 v144, 16, v216
	s_movk_i32 s0, 0x1ff
	s_cbranch_scc0 .Lsp2_go
	s_cmp_gt_i32 s13, 63
	s_cbranch_scc1 .LBB0_2933
	s_sub_i32 s13, s13, 32
	s_movk_i32 s100, 0x160
.Lsp2_go:
	v_add_u32_e32 v0, 64, v145
	v_xor_b32_e32 v1, 1, v216
	v_cmp_lt_i32_e32 vcc, v1, v0
	s_nop 1
	v_cndmask_b32_e32 v1, v216, v1, vcc
	v_lshlrev_b32_e32 v38, 2, v1
	v_xor_b32_e32 v1, 2, v216
	v_cmp_lt_i32_e32 vcc, v1, v0
	s_nop 1
	v_cndmask_b32_e32 v1, v216, v1, vcc
	v_lshlrev_b32_e32 v39, 2, v1
	v_xor_b32_e32 v1, 4, v216
	v_cmp_lt_i32_e32 vcc, v1, v0
	s_nop 1
	v_cndmask_b32_e32 v1, v216, v1, vcc
	v_lshlrev_b32_e32 v40, 2, v1
	v_xor_b32_e32 v1, 8, v216
	v_cmp_lt_i32_e32 vcc, v1, v0
	s_nop 1
	v_cndmask_b32_e32 v1, v216, v1, vcc
	v_cmp_lt_i32_e32 vcc, v144, v0
	v_lshlrev_b32_e32 v41, 2, v1
	s_nop 0
	v_cndmask_b32_e32 v0, v216, v144, vcc
	v_lshlrev_b32_e32 v42, 2, v0
	s_branch .LBB0_2912

.LBB0_2912:
	v_lshl_add_u64 v[248:249], v[162:163], 0, s[100:101]
	v_lshl_or_b32 v24, s13, 5, v201
	s_movk_i32 s1, 0x1600
	v_mad_i64_i32 v[60:61], s[2:3], v24, s1, v[164:165]
	v_lshl_add_u64 v[60:61], v[60:61], 0, s[100:101]
	global_load_dwordx4 v[64:67], v[248:249], off
	global_load_dwordx4 v[68:71], v[60:61], off
	global_load_dwordx4 v[72:75], v[248:249], off offset:32
	global_load_dwordx4 v[76:79], v[60:61], off offset:32
	global_load_dwordx4 v[80:83], v[248:249], off offset:64
	global_load_dwordx4 v[84:87], v[60:61], off offset:64
	global_load_dwordx4 v[88:91], v[248:249], off offset:96
	global_load_dwordx4 v[92:95], v[60:61], off offset:96
	global_load_dwordx4 v[96:99], v[248:249], off offset:128
	global_load_dwordx4 v[100:103], v[60:61], off offset:128
	global_load_dwordx4 v[104:107], v[248:249], off offset:160
	global_load_dwordx4 v[108:111], v[60:61], off offset:160
	global_load_dwordx4 v[112:115], v[248:249], off offset:192
	global_load_dwordx4 v[116:119], v[60:61], off offset:192
	global_load_dwordx4 v[120:123], v[248:249], off offset:224
	global_load_dwordx4 v[124:127], v[60:61], off offset:224
	global_load_dwordx4 v[136:139], v[248:249], off offset:256
	global_load_dwordx4 v[140:143], v[60:61], off offset:256
	global_load_dwordx4 v[148:151], v[248:249], off offset:288
	global_load_dwordx4 v[172:175], v[60:61], off offset:288
	global_load_dwordx4 v[176:179], v[248:249], off offset:320
	global_load_dwordx4 v[180:183], v[60:61], off offset:320
	v_add_u32_e32 v25, 0x8000, v204
	v_add_u32_e32 v44, v24, v202
	v_add_u32_e32 v46, 0x4000, v44
	v_ashrrev_i32_e32 v45, 31, v44
	v_ashrrev_i32_e32 v47, 31, v46
	v_lshl_add_u64 v[44:45], v[44:45], 2, s[92:93]
	v_lshl_add_u64 v[46:47], v[46:47], 2, s[92:93]
	global_load_dword v44, v[44:45], off
	s_nop 0
	global_load_dword v43, v[46:47], off
	v_add_u32_e32 v45, 0x8400, v204
	v_add_u32_e32 v46, 0x8800, v204
	v_add_u32_e32 v47, 0x8c00, v204
	s_waitcnt vmcnt(22)
	v_mfma_f32_32x32x16_bf16 v[0:15], v[64:67], v[68:71], 0
	s_waitcnt vmcnt(20)
	v_mfma_f32_32x32x16_bf16 v[0:15], v[72:75], v[76:79], v[0:15]
	s_waitcnt vmcnt(18)
	v_mfma_f32_32x32x16_bf16 v[0:15], v[80:83], v[84:87], v[0:15]
	s_waitcnt vmcnt(16)
	v_mfma_f32_32x32x16_bf16 v[0:15], v[88:91], v[92:95], v[0:15]
	s_waitcnt vmcnt(14)
	v_mfma_f32_32x32x16_bf16 v[0:15], v[96:99], v[100:103], v[0:15]
	s_waitcnt vmcnt(12)
	v_mfma_f32_32x32x16_bf16 v[0:15], v[104:107], v[108:111], v[0:15]
	s_waitcnt vmcnt(10)
	v_mfma_f32_32x32x16_bf16 v[0:15], v[112:115], v[116:119], v[0:15]
	s_waitcnt vmcnt(8)
	v_mfma_f32_32x32x16_bf16 v[0:15], v[120:123], v[124:127], v[0:15]
	s_waitcnt vmcnt(6)
	v_mfma_f32_32x32x16_bf16 v[0:15], v[136:139], v[140:143], v[0:15]
	s_waitcnt vmcnt(4)
	v_mfma_f32_32x32x16_bf16 v[0:15], v[148:151], v[172:175], v[0:15]
	s_waitcnt vmcnt(2)
	v_mfma_f32_32x32x16_bf16 v[0:15], v[176:179], v[180:183], v[0:15]
	s_waitcnt vmcnt(0)
	s_nop 11
	ds_write2_b32 v25, v0, v1 offset1:32
	ds_write2_b32 v25, v2, v3 offset0:64 offset1:96
	ds_write2_b32 v45, v4, v5 offset1:32
	ds_write2_b32 v45, v6, v7 offset0:64 offset1:96
	ds_write2_b32 v46, v8, v9 offset1:32
	ds_write2_b32 v46, v10, v11 offset0:64 offset1:96
	ds_write2_b32 v47, v12, v13 offset1:32
	ds_write2_b32 v47, v14, v15 offset0:64 offset1:96
	s_waitcnt lgkmcnt(0)
	s_barrier
	s_and_saveexec_b64 s[54:55], s[34:35]
	s_movk_i32 s1, 0x1080
	s_cbranch_execz .LBB0_2915
	s_mov_b64 s[2:3], 0
	v_mov_b32_e32 v0, v200

.LBB0_2915:
	s_or_b64 exec, exec, s[54:55]
	s_waitcnt lgkmcnt(0)
	s_barrier
	s_sub_u32 s54, s92, 0x24ac0000
	s_subb_u32 s55, s93, 0
	v_lshlrev_b32_e32 v48, 4, v200
	v_lshl_add_u32 v48, s13, 13, v48
	v_mov_b32_e32 v49, 0
	v_lshl_add_u64 v[48:49], v[48:49], 0, s[54:55]
	v_readlane_b32 s54, v254, 49
	s_nop 3
	s_add_i32 s54, s54, 1
	s_cmp_lg_u32 s100, 0
	s_cbranch_scc1 .Lsp2_hi
	s_mov_b32 s55, 0
.Lsp2_poll:
	global_load_dwordx2 v[50:51], v[48:49], off sc1
	global_load_dwordx2 v[52:53], v[48:49], off offset:8 sc1
	s_waitcnt vmcnt(0)
	v_cmp_ne_u32_e32 vcc, s54, v51
	v_cmp_ne_u32_e64 s[2:3], s54, v53
	s_or_b64 vcc, vcc, s[2:3]
	s_cbranch_vccz .Lsp2_got
	s_add_i32 s55, s55, 1
	s_cmp_lt_u32 s55, 0x4000
	s_cbranch_scc0 .Lsp2_got
	s_sleep 2
	s_branch .Lsp2_poll
.Lsp2_got:
	ds_read_b32 v0, v205
	v_ashrrev_i32_e32 v25, 31, v24
	s_waitcnt vmcnt(1) lgkmcnt(0)
	v_add_f32_e32 v0, v0, v50
	v_add_f32_e32 v1, v44, v0
	v_mul_f32_e32 v0, v1, v1
	ds_bpermute_b32 v0, v38, v0
	s_waitcnt lgkmcnt(0)
	v_fmac_f32_e32 v0, v1, v1
	s_waitcnt lgkmcnt(0)
	s_nop 1
	v_add_f32_dpp v0, v0, v0 quad_perm:[2,3,0,1] row_mask:0xf bank_mask:0xf
	s_waitcnt lgkmcnt(0)
	s_nop 1
	v_add_f32_dpp v0, v0, v0 row_half_mirror row_mask:0xf bank_mask:0xf
	s_waitcnt lgkmcnt(0)
	s_nop 1
	v_add_f32_dpp v0, v0, v0 row_mirror row_mask:0xf bank_mask:0xf
	v_mov_b32_e32 v2, v0
	s_nop 1
	v_permlane16_swap_b32_e32 v2, v0
	s_and_saveexec_b64 s[2:3], s[90:91]
	s_cbranch_execz .LBB0_2917
	s_waitcnt lgkmcnt(0)
	v_add_f32_e32 v0, v0, v2
	v_mul_f32_e32 v0, 0x4b800000, v0
	v_trunc_f32_e32 v0, v0
	v_mul_f32_e32 v2, 0x2f800000, v0
	v_floor_f32_e32 v3, v2
	v_fmac_f32_e32 v0, 0xcf800000, v3
	v_cvt_u32_f32_e32 v2, v0
	v_cvt_u32_f32_e32 v3, v3
	global_atomic_add_x2 v[166:167], v[2:3], off
.LBB0_2917:
	s_or_b64 exec, exec, s[2:3]
	ds_read_b32 v0, v27
	s_waitcnt vmcnt(0) lgkmcnt(0)
	v_add_f32_e32 v0, v0, v52
	v_add_f32_e32 v0, v43, v0
	v_mul_f32_e32 v2, v0, v0
	ds_bpermute_b32 v2, v38, v2
	s_waitcnt lgkmcnt(0)
	v_fmac_f32_e32 v2, v0, v0
	s_waitcnt lgkmcnt(0)
	s_nop 1
	v_add_f32_dpp v2, v2, v2 quad_perm:[2,3,0,1] row_mask:0xf bank_mask:0xf
	s_waitcnt lgkmcnt(0)
	s_nop 1
	v_add_f32_dpp v2, v2, v2 row_half_mirror row_mask:0xf bank_mask:0xf
	s_waitcnt lgkmcnt(0)
	s_nop 1
	v_add_f32_dpp v2, v2, v2 row_mirror row_mask:0xf bank_mask:0xf
	v_mov_b32_e32 v3, v2
	s_nop 1
	v_permlane16_swap_b32_e32 v3, v2
	s_and_saveexec_b64 s[2:3], s[90:91]
	s_cbranch_execz .LBB0_2919
	s_waitcnt lgkmcnt(0)
	v_add_f32_e32 v2, v2, v3
	v_mul_f32_e32 v2, 0x4b800000, v2
	v_trunc_f32_e32 v2, v2
	v_mul_f32_e32 v3, 0x2f800000, v2
	v_floor_f32_e32 v3, v3
	v_fmac_f32_e32 v2, 0xcf800000, v3
	v_cvt_u32_f32_e32 v2, v2
	v_cvt_u32_f32_e32 v3, v3
	global_atomic_add_x2 v[168:169], v[2:3], off

.Lsp2_hi:
	ds_read_b32 v50, v205
	ds_read_b32 v52, v27
	v_mov_b32_e32 v51, s54
	v_mov_b32_e32 v53, s54
	s_waitcnt lgkmcnt(0)
	global_store_dwordx2 v[48:49], v[50:51], off sc1
	global_store_dwordx2 v[48:49], v[52:53], off offset:8 sc1
	s_branch .LBB0_2933
